# attn loop: K reads batched, DMA issue moved into PV section, max tree via v_max3
# speedup vs baseline: 1.0076x; 1.0076x over previous
; __device__ __forceinline__ float swap_max(float m) { auto rr = __builtin_amdgcn_permlane32_swap(__float_as_uint(m), __float_as_uint(m), false, false); return fmaxf(__uint_as_float(rr[0]), __uint_as_float(rr[1])); }
; template <bool FIRST, bool HAS_PREV> ...
;     const unsigned kb_ = (unsigned)(unsigned long)kfr, vb_ = (unsigned)(unsigned long)vfr;
;     unsigned ka[4], va[4];
; #pragma unroll
;     for (int k = 0; k < 4; ++k) { ka[k] = kb_ + (unsigned)kofs[k]; va[k] = vb_ + (unsigned)vofs[k]; }
;     bf16x8 kf[4], vA[4], vB[4];
;     { const float nm = FIRST ? 0.f : -st.mrun;
; #pragma unroll
;       for (int i = 0; i < 16; ++i) { c0[i] = nm; c1[i] = nm; } }
; #pragma unroll
;     for (int ks = 0; ks < 2; ++ks) { DSR128(kf[2 * ks], ka[ks], 0); DSR128(kf[2 * ks + 1], ka[ks], 4096); }
;     asm volatile("s_waitcnt lgkmcnt(0)" : "+v"(kf[0]), "+v"(kf[1]), "+v"(kf[2]), "+v"(kf[3]));
; #pragma unroll
;     for (int ks = 0; ks < 2; ++ks) {
;         c0 = __builtin_amdgcn_mfma_f32_32x32x16_bf16(kf[2 * ks], qr[ks], c0, 0, 0, 0);
;         c1 = __builtin_amdgcn_mfma_f32_32x32x16_bf16(kf[2 * ks + 1], qr[ks], c1, 0, 0, 0);
;     }
;     __builtin_amdgcn_sched_barrier(0);
;     { bf16x8 kg[4];
; #pragma unroll
;       for (int ks = 0; ks < 2; ++ks) { DSR128(kg[2 * ks], ka[2 + ks], 0); DSR128(kg[2 * ks + 1], ka[2 + ks], 4096); }
;       asm volatile("s_waitcnt lgkmcnt(0)" : "+v"(kg[0]), "+v"(kg[1]), "+v"(kg[2]), "+v"(kg[3]));
; #pragma unroll
;       for (int ks = 0; ks < 2; ++ks) {
;           c0 = __builtin_amdgcn_mfma_f32_32x32x16_bf16(kg[2 * ks], qr[2 + ks], c0, 0, 0, 0);
;           c1 = __builtin_amdgcn_mfma_f32_32x32x16_bf16(kg[2 * ks + 1], qr[2 + ks], c1, 0, 0, 0);
;       } }
;     __builtin_amdgcn_sched_barrier(0);
;     if (HAS_PREV) {
; #pragma unroll
;         for (int e = 0; e < 4; ++e) DSR128(vA[e], va[0], e * 4096);
;     }
;     float mx = fmaxf(c0[0], c1[0]);
; #pragma unroll
;     for (int i = 1; i < 16; ++i) mx = fmaxf(mx, fmaxf(c0[i], c1[i]));
;     mx = swap_max(mx);
;     float a = 1.0f;
;     { const float dl = FIRST ? mx : ((mx > 8.0f) ? mx : 0.f);
;       if (FIRST || __any(dl != 0.f)) {
; #pragma unroll
;           for (int i = 0; i < 16; ++i) { c0[i] -= dl; c1[i] -= dl; }
;           st.mrun += dl; if (!FIRST) a = __builtin_amdgcn_exp2f(-dl);
;       } }
.LBB0_561:
	s_cmp_gt_u32 s53, 29
	s_cselect_b64 s[48:49], -1, 0
	s_mov_b32 s54, s74
	s_lshl_b32 s10, s54, 13
	s_lshl_b32 s11, s44, 14
	v_add_u32_e32 v80, s10, v209
	v_add_u32_e32 v81, s10, v211
	v_add_u32_e32 v82, s10, v213
	v_add_u32_e32 v83, s10, v215
	s_add_i32 s50, s11, 0x6000
	ds_read_b128 v[128:131], v80
	ds_read_b128 v[132:135], v80 offset:4096
	ds_read_b128 v[136:139], v81
	ds_read_b128 v[140:143], v81 offset:4096
	ds_read_b128 v[222:225], v82
	ds_read_b128 v[226:229], v82 offset:4096
	ds_read_b128 v[230:233], v83
	ds_read_b128 v[234:237], v83 offset:4096
	v_xor_b32_e32 v64, 0x80000000, v199
	v_mov_b32_e32 v65, v64
	v_mov_b32_e32 v66, v64
	v_mov_b32_e32 v67, v64
	v_mov_b32_e32 v68, v64
	v_mov_b32_e32 v69, v64
	v_mov_b32_e32 v70, v64
	v_mov_b32_e32 v71, v64
	v_mov_b32_e32 v72, v64
	v_mov_b32_e32 v73, v64
	v_mov_b32_e32 v74, v64
	v_mov_b32_e32 v75, v64
	v_mov_b32_e32 v76, v64
	v_mov_b32_e32 v77, v64
	v_mov_b32_e32 v78, v64
	v_mov_b32_e32 v79, v64
	v_add_u32_e32 v202, s50, v210
	s_waitcnt lgkmcnt(4)
	s_nop 0
	v_mfma_f32_32x32x16_bf16 v[80:95], v[128:131], v[96:99], v[64:79]
	v_mfma_f32_32x32x16_bf16 v[64:79], v[132:135], v[96:99], v[64:79]
	v_mfma_f32_32x32x16_bf16 v[80:95], v[136:139], v[100:103], v[80:95]
	v_mfma_f32_32x32x16_bf16 v[64:79], v[140:143], v[100:103], v[64:79]
	s_waitcnt lgkmcnt(0)
	v_mfma_f32_32x32x16_bf16 v[80:95], v[222:225], v[104:107], v[80:95]
	v_mfma_f32_32x32x16_bf16 v[64:79], v[226:229], v[104:107], v[64:79]
	v_mfma_f32_32x32x16_bf16 v[80:95], v[230:233], v[108:111], v[80:95]
	v_mfma_f32_32x32x16_bf16 v[64:79], v[234:237], v[108:111], v[64:79]
	ds_read_b128 v[140:143], v202
	ds_read_b128 v[136:139], v202 offset:4096
	ds_read_b128 v[132:135], v202 offset:8192
	ds_read_b128 v[128:131], v202 offset:12288
	s_nop 6
	v_max3_f32 v202, v80, v81, v82
	v_max3_f32 v202, v202, v83, v84
	v_max3_f32 v202, v202, v85, v86
	v_max3_f32 v202, v202, v87, v88
	v_max3_f32 v202, v202, v89, v90
	v_max3_f32 v202, v202, v91, v92
	v_max3_f32 v202, v202, v93, v94
	v_max3_f32 v204, v64, v65, v66
	v_max3_f32 v204, v204, v67, v68
	v_max3_f32 v204, v204, v69, v70
	v_max3_f32 v204, v204, v71, v72
	v_max3_f32 v204, v204, v73, v74
	v_max3_f32 v204, v204, v75, v76
	v_max3_f32 v204, v204, v77, v78
	v_max3_f32 v202, v202, v95, v79
	v_max_f32_e32 v202, v202, v204
	v_mov_b32_e32 v204, v202
	s_nop 1
	v_permlane32_swap_b32_e32 v202, v204
	v_max_f32_e32 v204, v204, v204
	v_max_f32_e32 v202, v202, v202
	v_max_f32_e32 v202, v202, v204
	v_cmp_lt_f32_e32 vcc, s84, v202
	s_nop 1
	v_cndmask_b32_e32 v204, 0, v202, vcc
	v_cmp_neq_f32_e32 vcc, 0, v204
	s_cbranch_vccz .LBB0_567
	v_exp_f32_e64 v202, -v204
	v_pk_add_f32 v[80:81], v[80:81], v[204:205] op_sel_hi:[1,0] neg_lo:[0,1] neg_hi:[0,1]
	v_pk_add_f32 v[82:83], v[82:83], v[204:205] op_sel_hi:[1,0] neg_lo:[0,1] neg_hi:[0,1]
	v_pk_add_f32 v[84:85], v[84:85], v[204:205] op_sel_hi:[1,0] neg_lo:[0,1] neg_hi:[0,1]
	v_pk_add_f32 v[86:87], v[86:87], v[204:205] op_sel_hi:[1,0] neg_lo:[0,1] neg_hi:[0,1]
	v_pk_add_f32 v[88:89], v[88:89], v[204:205] op_sel_hi:[1,0] neg_lo:[0,1] neg_hi:[0,1]
	v_pk_add_f32 v[90:91], v[90:91], v[204:205] op_sel_hi:[1,0] neg_lo:[0,1] neg_hi:[0,1]
	v_pk_add_f32 v[92:93], v[92:93], v[204:205] op_sel_hi:[1,0] neg_lo:[0,1] neg_hi:[0,1]
	v_pk_add_f32 v[94:95], v[94:95], v[204:205] op_sel_hi:[1,0] neg_lo:[0,1] neg_hi:[0,1]
	v_sub_f32_e32 v79, v79, v204
	v_sub_f32_e32 v78, v78, v204
	v_sub_f32_e32 v77, v77, v204
	v_sub_f32_e32 v76, v76, v204
	v_sub_f32_e32 v75, v75, v204
	v_sub_f32_e32 v74, v74, v204
	v_sub_f32_e32 v73, v73, v204
	v_sub_f32_e32 v72, v72, v204
	v_sub_f32_e32 v71, v71, v204
	v_sub_f32_e32 v70, v70, v204
	v_sub_f32_e32 v69, v69, v204
	v_sub_f32_e32 v68, v68, v204
	v_sub_f32_e32 v67, v67, v204
	v_sub_f32_e32 v66, v66, v204
	v_sub_f32_e32 v65, v65, v204
	v_sub_f32_e32 v64, v64, v204
	v_add_f32_e32 v199, v199, v204
	s_branch .LBB0_568

; #define DSR128(dst, addr, off) asm volatile("ds_read_b128 %0, %1 offset:%2" : "=&v"(dst) : "v"(addr), "i"(off))
; #define ATT_EXPS(E) do { _Pragma("unroll") for (int j = 0; j < 8; ++j) { const int i = (E) * 8 + j; \
;         if (i < 16) { c0[i] = __builtin_amdgcn_exp2f(c0[i]); ps += c0[i]; } else { c1[i - 16] = __builtin_amdgcn_exp2f(c1[i - 16]); ps += c1[i - 16]; } } \
;         asm volatile("" : "+v"(c0), "+v"(c1), "+v"(ps)); __builtin_amdgcn_sched_barrier(0); } while (0)
; #define ATT_PV(KK, VF) do { _Pragma("unroll") for (int e = 0; e < 4; ++e) o[e] = __builtin_amdgcn_mfma_f32_32x32x16_bf16(VF[e], pbp[KK], o[e], 0, 0, 0); } while (0)
; #define ATT_TIE(N, VF) asm volatile("s_waitcnt lgkmcnt(" #N ")" : "+v"(VF[0]), "+v"(VF[1]), "+v"(VF[2]), "+v"(VF[3]))
; template <bool FIRST, bool HAS_PREV> ...
;     ...
;     if (HAS_PREV) {
;         __builtin_amdgcn_sched_barrier(0);
; #pragma unroll
;         for (int e = 0; e < 4; ++e) DSR128(vB[e], va[1], e * 4096);
;         ATT_TIE(4, vA); ATT_PV(0, vA); ATT_EXPS(0);
; #pragma unroll
;         for (int e = 0; e < 4; ++e) DSR128(vA[e], va[2], e * 4096);
;         ATT_TIE(4, vB); ATT_PV(1, vB); ATT_EXPS(1);
; #pragma unroll
;         for (int e = 0; e < 4; ++e) DSR128(vB[e], va[3], e * 4096);
;         ATT_TIE(4, vA); ATT_PV(2, vA); ATT_EXPS(2);
;         ATT_TIE(0, vB); ATT_PV(3, vB); ATT_EXPS(3);
.LBB0_568:
	v_add_u32_e32 v204, s50, v212
	v_add_u32_e32 v221, s50, v214
	v_add_u32_e32 v238, s50, v216
	v_exp_f32_e32 v80, v80
	v_exp_f32_e32 v81, v81
	v_exp_f32_e32 v82, v82
	ds_read_b128 v[222:225], v204 offset:0
	ds_read_b128 v[226:229], v204 offset:0x1000
	ds_read_b128 v[230:233], v204 offset:0x2000
	ds_read_b128 v[234:237], v204 offset:0x3000
	s_waitcnt lgkmcnt(4)
	v_exp_f32_e32 v83, v83
	v_mfma_f32_32x32x16_bf16 v[48:63], v[140:143], v[124:127], v[48:63]
	v_exp_f32_e32 v84, v84
	v_exp_f32_e32 v85, v85
	v_exp_f32_e32 v86, v86
	v_exp_f32_e32 v87, v87
	v_mfma_f32_32x32x16_bf16 v[32:47], v[136:139], v[124:127], v[32:47]
	v_add_f32_e32 v136, 0, v80
	v_add_f32_e32 v136, v81, v136
	v_add_f32_e32 v136, v82, v136
	v_add_f32_e32 v136, v83, v136
	v_mfma_f32_32x32x16_bf16 v[16:31], v[132:135], v[124:127], v[16:31]
	v_add_f32_e32 v132, v84, v136
	v_add_f32_e32 v132, v85, v132
	v_add_f32_e32 v132, v86, v132
	v_add_f32_e32 v140, v87, v132
	v_mfma_f32_32x32x16_bf16 v[0:15], v[128:131], v[124:127], v[0:15]
	s_cmp_gt_u32 s53, 29
	s_cbranch_scc1 .Latt_nok
	s_lshl_b32 s10, s44, 13
	s_add_i32 m0, s33, s10
	s_nop 0
	global_load_lds_dwordx4 v[200:201], off
.Latt_nok:
	v_exp_f32_e32 v88, v88
	v_exp_f32_e32 v89, v89
	v_exp_f32_e32 v90, v90
	v_exp_f32_e32 v91, v91
	ds_read_b128 v[124:127], v221 offset:0
	ds_read_b128 v[128:131], v221 offset:0x1000
	ds_read_b128 v[132:135], v221 offset:0x2000
	ds_read_b128 v[136:139], v221 offset:0x3000
	s_waitcnt lgkmcnt(4)
	v_add_f32_e32 v140, v140, v88
	v_mfma_f32_32x32x16_bf16 v[48:63], v[222:225], v[120:123], v[48:63]
	v_exp_f32_e32 v92, v92
	v_add_f32_e32 v140, v89, v140
	v_exp_f32_e32 v93, v93
	v_add_f32_e32 v140, v90, v140
	v_exp_f32_e32 v94, v94
	v_add_f32_e32 v140, v91, v140
	v_exp_f32_e32 v95, v95
	v_mfma_f32_32x32x16_bf16 v[32:47], v[226:229], v[120:123], v[32:47]
	v_add_f32_e32 v140, v92, v140
	v_add_f32_e32 v140, v93, v140
	v_add_f32_e32 v140, v94, v140
	v_add_f32_e32 v204, v95, v140
	v_mfma_f32_32x32x16_bf16 v[16:31], v[230:233], v[120:123], v[16:31]
	v_mfma_f32_32x32x16_bf16 v[0:15], v[234:237], v[120:123], v[0:15]
	s_cmp_eq_u32 s46, 0x78000
	s_cbranch_scc1 .Latt_nov
	s_lshl_b32 s10, s52, 14
	s_add_i32 s10, s33, s10
	v_lshl_add_u64 v[240:241], v[196:197], 0, s[46:47]
	s_add_i32 m0, s10, 0x6000
	v_lshl_add_u64 v[242:243], v[240:241], 0, s[66:67]
	s_add_i32 s10, s10, 0x8000
	v_lshl_add_u64 v[240:241], v[240:241], 0, s[80:81]
	global_load_lds_dwordx4 v[242:243], off
	s_mov_b32 m0, s10
	s_nop 0
	global_load_lds_dwordx4 v[240:241], off
.Latt_nov:
	v_exp_f32_e32 v64, v64
	v_exp_f32_e32 v65, v65
	v_exp_f32_e32 v66, v66
	ds_read_b128 v[120:123], v238 offset:0
	ds_read_b128 v[140:143], v238 offset:0x1000
	ds_read_b128 v[222:225], v238 offset:0x2000
	ds_read_b128 v[226:229], v238 offset:0x3000
	s_waitcnt lgkmcnt(4)
	v_exp_f32_e32 v67, v67
	v_mfma_f32_32x32x16_bf16 v[48:63], v[124:127], v[116:119], v[48:63]
	v_add_f32_e32 v124, v204, v64
	v_exp_f32_e32 v68, v68
	v_add_f32_e32 v124, v65, v124
	v_exp_f32_e32 v69, v69
	v_add_f32_e32 v124, v66, v124
	v_exp_f32_e32 v70, v70
	v_add_f32_e32 v124, v67, v124
	v_mfma_f32_32x32x16_bf16 v[32:47], v[128:131], v[116:119], v[32:47]
	v_exp_f32_e32 v71, v71
	v_add_f32_e32 v124, v68, v124
	v_add_f32_e32 v124, v69, v124
	v_add_f32_e32 v124, v70, v124
	v_add_f32_e32 v124, v71, v124
	v_mfma_f32_32x32x16_bf16 v[16:31], v[132:135], v[116:119], v[16:31]
	v_mfma_f32_32x32x16_bf16 v[0:15], v[136:139], v[116:119], v[0:15]
	v_exp_f32_e32 v72, v72
	v_exp_f32_e32 v73, v73
	v_exp_f32_e32 v74, v74
	v_exp_f32_e32 v75, v75
	s_waitcnt lgkmcnt(0)
	v_add_f32_e32 v116, v124, v72
	v_mfma_f32_32x32x16_bf16 v[48:63], v[120:123], v[112:115], v[48:63]
	v_exp_f32_e32 v76, v76
	v_add_f32_e32 v116, v73, v116
	v_exp_f32_e32 v77, v77
	v_add_f32_e32 v116, v74, v116
	v_exp_f32_e32 v78, v78
	v_add_f32_e32 v116, v75, v116
	v_exp_f32_e32 v79, v79
	v_mfma_f32_32x32x16_bf16 v[32:47], v[140:143], v[112:115], v[32:47]
	v_add_f32_e32 v116, v76, v116
	v_add_f32_e32 v116, v77, v116
	v_add_f32_e32 v116, v78, v116
	v_add_f32_e32 v128, v79, v116
	v_mfma_f32_32x32x16_bf16 v[16:31], v[222:225], v[112:115], v[16:31]
	v_mfma_f32_32x32x16_bf16 v[0:15], v[226:229], v[112:115], v[0:15]
	v_cmp_neq_f32_e32 vcc, 1.0, v202
	s_cbranch_vccz .LBB0_570
	v_pk_mul_f32 v[62:63], v[202:203], v[62:63] op_sel_hi:[0,1]
	v_pk_mul_f32 v[60:61], v[202:203], v[60:61] op_sel_hi:[0,1]
	v_pk_mul_f32 v[58:59], v[202:203], v[58:59] op_sel_hi:[0,1]
	v_pk_mul_f32 v[56:57], v[202:203], v[56:57] op_sel_hi:[0,1]
	v_pk_mul_f32 v[54:55], v[202:203], v[54:55] op_sel_hi:[0,1]
	v_pk_mul_f32 v[52:53], v[202:203], v[52:53] op_sel_hi:[0,1]
	v_pk_mul_f32 v[50:51], v[202:203], v[50:51] op_sel_hi:[0,1]
	v_pk_mul_f32 v[48:49], v[202:203], v[48:49] op_sel_hi:[0,1]
	v_pk_mul_f32 v[46:47], v[202:203], v[46:47] op_sel_hi:[0,1]
	v_pk_mul_f32 v[44:45], v[202:203], v[44:45] op_sel_hi:[0,1]
	v_pk_mul_f32 v[42:43], v[202:203], v[42:43] op_sel_hi:[0,1]
	v_pk_mul_f32 v[40:41], v[202:203], v[40:41] op_sel_hi:[0,1]
	v_pk_mul_f32 v[38:39], v[202:203], v[38:39] op_sel_hi:[0,1]
	v_pk_mul_f32 v[36:37], v[202:203], v[36:37] op_sel_hi:[0,1]
	v_pk_mul_f32 v[34:35], v[202:203], v[34:35] op_sel_hi:[0,1]
	v_pk_mul_f32 v[32:33], v[202:203], v[32:33] op_sel_hi:[0,1]
	v_pk_mul_f32 v[30:31], v[202:203], v[30:31] op_sel_hi:[0,1]
	v_pk_mul_f32 v[28:29], v[202:203], v[28:29] op_sel_hi:[0,1]
	v_pk_mul_f32 v[26:27], v[202:203], v[26:27] op_sel_hi:[0,1]
	v_pk_mul_f32 v[24:25], v[202:203], v[24:25] op_sel_hi:[0,1]
	v_pk_mul_f32 v[22:23], v[202:203], v[22:23] op_sel_hi:[0,1]
	v_pk_mul_f32 v[20:21], v[202:203], v[20:21] op_sel_hi:[0,1]
	v_pk_mul_f32 v[18:19], v[202:203], v[18:19] op_sel_hi:[0,1]
	v_pk_mul_f32 v[16:17], v[202:203], v[16:17] op_sel_hi:[0,1]
	v_pk_mul_f32 v[14:15], v[202:203], v[14:15] op_sel_hi:[0,1]
	v_pk_mul_f32 v[12:13], v[202:203], v[12:13] op_sel_hi:[0,1]
	v_pk_mul_f32 v[10:11], v[202:203], v[10:11] op_sel_hi:[0,1]
	v_pk_mul_f32 v[8:9], v[202:203], v[8:9] op_sel_hi:[0,1]
	v_pk_mul_f32 v[6:7], v[202:203], v[6:7] op_sel_hi:[0,1]
	v_pk_mul_f32 v[4:5], v[202:203], v[4:5] op_sel_hi:[0,1]
	v_pk_mul_f32 v[2:3], v[202:203], v[2:3] op_sel_hi:[0,1]
	v_pk_mul_f32 v[0:1], v[202:203], v[0:1] op_sel_hi:[0,1]

; __global__ void __launch_bounds__(512, 2) fwd_mega(Args a) {
	.amdhsa_kernel _Z8fwd_mega4Args
		.amdhsa_group_segment_fixed_size 0
		.amdhsa_private_segment_fixed_size 0
		.amdhsa_kernarg_size 480
		.amdhsa_user_sgpr_count 2
		.amdhsa_user_sgpr_dispatch_ptr 0
		.amdhsa_user_sgpr_queue_ptr 0
		.amdhsa_user_sgpr_kernarg_segment_ptr 1
		.amdhsa_user_sgpr_dispatch_id 0
		.amdhsa_user_sgpr_kernarg_preload_length 0
		.amdhsa_user_sgpr_kernarg_preload_offset 0
		.amdhsa_user_sgpr_private_segment_size 0
		.amdhsa_uses_dynamic_stack 0
		.amdhsa_enable_private_segment 0
		.amdhsa_system_sgpr_workgroup_id_x 1
		.amdhsa_system_sgpr_workgroup_id_y 0
		.amdhsa_system_sgpr_workgroup_id_z 0
		.amdhsa_system_sgpr_workgroup_info 0
		.amdhsa_system_vgpr_workitem_id 2
		.amdhsa_next_free_vgpr 248
		.amdhsa_next_free_sgpr 98
		.amdhsa_accum_offset 248
		.amdhsa_reserve_vcc 1
		.amdhsa_float_round_mode_32 0
		.amdhsa_float_round_mode_16_64 0
		.amdhsa_float_denorm_mode_32 3
		.amdhsa_float_denorm_mode_16_64 3
		.amdhsa_dx10_clamp 1
		.amdhsa_ieee_mode 1
		.amdhsa_fp16_overflow 0
		.amdhsa_tg_split 0
		.amdhsa_exception_fp_ieee_invalid_op 0
		.amdhsa_exception_fp_denorm_src 0
		.amdhsa_exception_fp_ieee_div_zero 0
		.amdhsa_exception_fp_ieee_overflow 0
		.amdhsa_exception_fp_ieee_underflow 0
		.amdhsa_exception_fp_ieee_inexact 0
		.amdhsa_exception_int_div_zero 0
	.end_amdhsa_kernel

; __global__ void __launch_bounds__(512, 2) fwd_mega(Args a) {
.Lfunc_end0:
	.size	_Z8fwd_mega4Args, .Lfunc_end0-_Z8fwd_mega4Args
	.set _Z8fwd_mega4Args.num_vgpr, 248
	.set _Z8fwd_mega4Args.num_agpr, 0
	.set _Z8fwd_mega4Args.numbered_sgpr, 98
	.set _Z8fwd_mega4Args.num_named_barrier, 0
	.set _Z8fwd_mega4Args.private_seg_size, 0
	.set _Z8fwd_mega4Args.uses_vcc, 1
	.set _Z8fwd_mega4Args.uses_flat_scratch, 0
	.set _Z8fwd_mega4Args.has_dyn_sized_stack, 0
	.set _Z8fwd_mega4Args.has_recursion, 0
	.set _Z8fwd_mega4Args.has_indirect_call, 0

; __global__ void __launch_bounds__(512, 2) fwd_mega(Args a) {
amdhsa.kernels:
  - .agpr_count:     0
    .args:
      - .offset:         0
        .size:           224
        .value_kind:     by_value
      - .offset:         224
        .size:           4
        .value_kind:     hidden_block_count_x
      - .offset:         228
        .size:           4
        .value_kind:     hidden_block_count_y
      - .offset:         232
        .size:           4
        .value_kind:     hidden_block_count_z
      - .offset:         236
        .size:           2
        .value_kind:     hidden_group_size_x
      - .offset:         238
        .size:           2
        .value_kind:     hidden_group_size_y
      - .offset:         240
        .size:           2
        .value_kind:     hidden_group_size_z
      - .offset:         242
        .size:           2
        .value_kind:     hidden_remainder_x
      - .offset:         244
        .size:           2
        .value_kind:     hidden_remainder_y
      - .offset:         246
        .size:           2
        .value_kind:     hidden_remainder_z
      - .offset:         264
        .size:           8
        .value_kind:     hidden_global_offset_x
      - .offset:         272
        .size:           8
        .value_kind:     hidden_global_offset_y
      - .offset:         280
        .size:           8
        .value_kind:     hidden_global_offset_z
      - .offset:         288
        .size:           2
        .value_kind:     hidden_grid_dims
      - .offset:         312
        .size:           8
        .value_kind:     hidden_multigrid_sync_arg
      - .offset:         344
        .size:           4
        .value_kind:     hidden_dynamic_lds_size
    .group_segment_fixed_size: 0
    .kernarg_segment_align: 8
    .kernarg_segment_size: 480
    .language:       OpenCL C
    .language_version:
      - 2
      - 0
    .max_flat_workgroup_size: 512
    .name:           _Z8fwd_mega4Args
    .private_segment_fixed_size: 0
    .sgpr_count:     104
    .sgpr_spill_count: 14
    .symbol:         _Z8fwd_mega4Args.kd
    .uniform_work_group_size: 1
    .uses_dynamic_stack: false
    .vgpr_count:     248
    .vgpr_spill_count: 0
    .wavefront_size: 64
